# P2 finalizes: row-scattered gate loads widened from dwordx2 to dwordx4 in block pairs (12 fewer loads per workgroup), redistributed with v_permlane16_swap after the wait
# speedup vs baseline: 1.0055x; 1.0045x over previous
; template <bool DIFF>
; __device__ __forceinline__ void attn_item(LAS unsigned char* lds, const bf16_t* Z, bf16_t* MIX, int b, int h, int t, float lam, float shift, const float* gain, int tid, int wid, int lane) {
;     ...
;     float inv0 = 1.f, inv1 = 0.f;
;     if (DIFF) {
; #pragma unroll
;         for (int c = 0; c < NC; ++c) l[c] = quad_sum(l[c]);
;         inv0 = 1.0f / l[0]; inv1 = lam / l[NC - 1];
;     }
;     float ss = 0.f;
; #pragma unroll
;     for (int eb = 0; eb < 8; ++eb)
; #pragma unroll
;         for (int i = 0; i < 4; ++i) { float v = O[0][eb][i] * inv0; if (DIFF) v -= O[NC - 1][eb][i] * inv1; O[0][eb][i] = v; ss += v * v; }
;     ss = quad_sum(ss);
;     const float r = rsqrtf(ss * (1.0f / 128.0f) + EPS) * (DIFF ? 0.8f : 1.0f);
;     const int row = row0 + q16;
;     const bf16_t* gp = Z + (size_t)row * DIN + gcol + 4 * quad;
;     bf16_t* op = MIX + (size_t)row * DM + (DIFF ? 1024 : 0) + 128 * h + 4 * quad;
; #pragma unroll
;     for (int eb = 0; eb < 8; ++eb) {
;         const u32x2 gw = *(const u32x2*)(gp + 16 * eb);
;         const f32x4 gn = *(const f32x4*)(gain + 16 * eb + 4 * quad);
.Ldx_done:
.LBB0_574:
	s_waitcnt lgkmcnt(0)
	ds_swizzle_b32 v68, v131 offset:swizzle(SWAP,16)
	ds_swizzle_b32 v69, v130 offset:swizzle(SWAP,16)
	v_ashrrev_i32_e32 v129, 31, v128
	v_lshlrev_b64 v[80:81], 1, v[128:129]
	s_lshl_b32 s86, s80, 1
	s_waitcnt lgkmcnt(0)
	v_add_f32_e32 v68, v131, v68
	v_mov_b32_e32 v70, v68
	s_nop 1
	v_permlane32_swap_b32_e32 v68, v70
	v_add_f32_e32 v68, v68, v70
	v_div_scale_f32 v70, s[0:1], v68, v68, 1.0
	v_rcp_f32_e32 v72, v70
	v_add_f32_e32 v69, v130, v69
	v_mov_b32_e32 v71, v69
	s_nop 1
	v_permlane32_swap_b32_e32 v69, v71
	v_add_f32_e32 v69, v69, v71
	v_fma_f32 v71, -v70, v72, 1.0
	v_fmac_f32_e32 v72, v71, v72
	v_div_scale_f32 v71, vcc, 1.0, v68, 1.0
	v_mul_f32_e32 v73, v71, v72
	v_fma_f32 v74, -v70, v73, v71
	v_fmac_f32_e32 v73, v74, v72
	v_fma_f32 v70, -v70, v73, v71
	v_div_scale_f32 v71, s[0:1], v69, v69, s28
	v_rcp_f32_e32 v74, v71
	v_div_fmas_f32 v70, v70, v72, v73
	v_div_fixup_f32 v76, v70, v68, 1.0
	s_movk_i32 s0, 0x3000
	v_fma_f32 v68, -v71, v74, 1.0
	v_fmac_f32_e32 v74, v68, v74
	v_div_scale_f32 v68, vcc, s28, v69, s28
	v_mul_f32_e32 v70, v68, v74
	v_fma_f32 v72, -v71, v70, v68
	v_fmac_f32_e32 v70, v72, v74
	v_fma_f32 v68, -v71, v70, v68
	v_lshl_add_u64 v[72:73], v[126:127], 0, v[80:81]
	v_div_fmas_f32 v68, v68, v74, v70
	v_lshl_add_u64 v[70:71], v[72:73], 0, s[92:93]
	v_add_co_u32_e32 v72, vcc, s0, v72
	v_div_fixup_f32 v78, v68, v69, s28
	v_lshlrev_b64 v[68:69], 12, v[124:125]
	v_addc_co_u32_e32 v73, vcc, 0, v73, vcc
	v_lshl_add_u64 v[82:83], s[88:89], 0, v[68:69]
	v_lshl_add_u64 v[68:69], v[128:129], 2, s[84:85]
	v_mbcnt_lo_u32_b32 v150, -1, 0
	v_mbcnt_hi_u32_b32 v150, -1, v150
	v_and_b32_e32 v150, 16, v150
	v_lshrrev_b32_e32 v151, 1, v150
	v_add_u32_e32 v150, v150, v151
	v_mov_b32_e32 v151, 0
	v_lshl_add_u64 v[152:153], v[70:71], 0, v[150:151]
	global_load_dwordx4 v[84:87], v[68:69], off
	global_load_dwordx4 v[116:119], v[152:153], off
	global_load_dwordx4 v[88:91], v[68:69], off offset:64
	global_load_dwordx4 v[92:95], v[68:69], off offset:128
	global_load_dwordx4 v[120:123], v[152:153], off offset:64
	global_load_dwordx4 v[96:99], v[68:69], off offset:192
	global_load_dwordx4 v[100:103], v[68:69], off offset:256
	global_load_dwordx4 v[132:135], v[152:153], off offset:128
	global_load_dwordx4 v[104:107], v[68:69], off offset:320
	global_load_dwordx4 v[108:111], v[68:69], off offset:384
	global_load_dwordx4 v[136:139], v[152:153], off offset:192
	global_load_dwordx4 v[112:115], v[68:69], off offset:448
	v_pk_mul_f32 v[56:57], v[56:57], v[78:79] op_sel_hi:[1,0]
	v_pk_mul_f32 v[58:59], v[58:59], v[78:79] op_sel_hi:[1,0]
	v_pk_fma_f32 v[56:57], v[64:65], v[76:77], v[56:57] op_sel_hi:[1,0,1] neg_lo:[0,0,1] neg_hi:[0,0,1]
	v_pk_fma_f32 v[58:59], v[66:67], v[76:77], v[58:59] op_sel_hi:[1,0,1] neg_lo:[0,0,1] neg_hi:[0,0,1]
	v_pk_mul_f32 v[64:65], v[56:57], v[56:57]
	v_pk_mul_f32 v[66:67], v[58:59], v[58:59]
	v_pk_mul_f32 v[52:53], v[52:53], v[78:79] op_sel_hi:[1,0]
	v_add_f32_e32 v64, v64, v65
	v_pk_fma_f32 v[52:53], v[60:61], v[76:77], v[52:53] op_sel_hi:[1,0,1] neg_lo:[0,0,1] neg_hi:[0,0,1]
	v_add_f32_e32 v64, v66, v64
	v_pk_mul_f32 v[54:55], v[54:55], v[78:79] op_sel_hi:[1,0]
	v_pk_mul_f32 v[60:61], v[52:53], v[52:53]
	v_add_f32_e32 v64, v67, v64
	v_pk_fma_f32 v[54:55], v[62:63], v[76:77], v[54:55] op_sel_hi:[1,0,1] neg_lo:[0,0,1] neg_hi:[0,0,1]
	v_add_f32_e32 v60, v60, v64
	v_pk_mul_f32 v[62:63], v[54:55], v[54:55]
	v_pk_mul_f32 v[44:45], v[44:45], v[78:79] op_sel_hi:[1,0]
	v_add_f32_e32 v60, v61, v60
	v_pk_fma_f32 v[44:45], v[48:49], v[76:77], v[44:45] op_sel_hi:[1,0,1] neg_lo:[0,0,1] neg_hi:[0,0,1]
	v_add_f32_e32 v60, v62, v60
	v_pk_mul_f32 v[46:47], v[46:47], v[78:79] op_sel_hi:[1,0]
	v_pk_mul_f32 v[48:49], v[44:45], v[44:45]
	v_add_f32_e32 v60, v63, v60
	v_pk_fma_f32 v[46:47], v[50:51], v[76:77], v[46:47] op_sel_hi:[1,0,1] neg_lo:[0,0,1] neg_hi:[0,0,1]
	v_add_f32_e32 v48, v48, v60
	v_pk_mul_f32 v[50:51], v[46:47], v[46:47]
	v_pk_mul_f32 v[36:37], v[36:37], v[78:79] op_sel_hi:[1,0]
	v_add_f32_e32 v48, v49, v48
	v_pk_fma_f32 v[36:37], v[40:41], v[76:77], v[36:37] op_sel_hi:[1,0,1] neg_lo:[0,0,1] neg_hi:[0,0,1]
	v_add_f32_e32 v48, v50, v48
	v_pk_mul_f32 v[38:39], v[38:39], v[78:79] op_sel_hi:[1,0]
	v_pk_mul_f32 v[40:41], v[36:37], v[36:37]
	v_add_f32_e32 v48, v51, v48
	v_pk_fma_f32 v[38:39], v[42:43], v[76:77], v[38:39] op_sel_hi:[1,0,1] neg_lo:[0,0,1] neg_hi:[0,0,1]
	v_add_f32_e32 v40, v40, v48
	v_pk_mul_f32 v[42:43], v[38:39], v[38:39]
	v_pk_mul_f32 v[28:29], v[28:29], v[78:79] op_sel_hi:[1,0]
	v_add_f32_e32 v40, v41, v40
	v_pk_fma_f32 v[28:29], v[32:33], v[76:77], v[28:29] op_sel_hi:[1,0,1] neg_lo:[0,0,1] neg_hi:[0,0,1]
	v_add_f32_e32 v40, v42, v40
	v_pk_mul_f32 v[30:31], v[30:31], v[78:79] op_sel_hi:[1,0]
	v_pk_mul_f32 v[32:33], v[28:29], v[28:29]
	v_add_f32_e32 v40, v43, v40
	v_pk_fma_f32 v[30:31], v[34:35], v[76:77], v[30:31] op_sel_hi:[1,0,1] neg_lo:[0,0,1] neg_hi:[0,0,1]
	v_add_f32_e32 v32, v32, v40
	v_pk_mul_f32 v[34:35], v[30:31], v[30:31]
	v_pk_mul_f32 v[20:21], v[20:21], v[78:79] op_sel_hi:[1,0]
	v_add_f32_e32 v32, v33, v32
	v_pk_fma_f32 v[20:21], v[24:25], v[76:77], v[20:21] op_sel_hi:[1,0,1] neg_lo:[0,0,1] neg_hi:[0,0,1]
	v_add_f32_e32 v32, v34, v32
	v_pk_mul_f32 v[22:23], v[22:23], v[78:79] op_sel_hi:[1,0]
	v_pk_mul_f32 v[24:25], v[20:21], v[20:21]
	v_add_f32_e32 v32, v35, v32
	v_pk_fma_f32 v[22:23], v[26:27], v[76:77], v[22:23] op_sel_hi:[1,0,1] neg_lo:[0,0,1] neg_hi:[0,0,1]
	v_add_f32_e32 v24, v24, v32
	v_pk_mul_f32 v[26:27], v[22:23], v[22:23]
	v_pk_mul_f32 v[12:13], v[12:13], v[78:79] op_sel_hi:[1,0]
	v_add_f32_e32 v24, v25, v24
	v_pk_fma_f32 v[12:13], v[16:17], v[76:77], v[12:13] op_sel_hi:[1,0,1] neg_lo:[0,0,1] neg_hi:[0,0,1]
	v_add_f32_e32 v24, v26, v24
	v_pk_mul_f32 v[14:15], v[14:15], v[78:79] op_sel_hi:[1,0]
	v_pk_mul_f32 v[16:17], v[12:13], v[12:13]
	v_add_f32_e32 v24, v27, v24
	v_pk_fma_f32 v[14:15], v[18:19], v[76:77], v[14:15] op_sel_hi:[1,0,1] neg_lo:[0,0,1] neg_hi:[0,0,1]
	v_add_f32_e32 v16, v16, v24
	v_pk_mul_f32 v[18:19], v[14:15], v[14:15]
	v_pk_mul_f32 v[4:5], v[4:5], v[78:79] op_sel_hi:[1,0]
	v_add_f32_e32 v16, v17, v16
	v_pk_fma_f32 v[8:9], v[8:9], v[76:77], v[4:5] op_sel_hi:[1,0,1] neg_lo:[0,0,1] neg_hi:[0,0,1]
	v_add_f32_e32 v16, v18, v16
	v_pk_mul_f32 v[6:7], v[6:7], v[78:79] op_sel_hi:[1,0]
	v_pk_mul_f32 v[4:5], v[8:9], v[8:9]
	v_add_f32_e32 v16, v19, v16
	v_pk_fma_f32 v[10:11], v[10:11], v[76:77], v[6:7] op_sel_hi:[1,0,1] neg_lo:[0,0,1] neg_hi:[0,0,1]
	v_add_f32_e32 v4, v4, v16
	v_pk_mul_f32 v[6:7], v[10:11], v[10:11]
	v_add_f32_e32 v4, v5, v4
	v_add_f32_e32 v4, v6, v4
	v_add_f32_e32 v6, v7, v4
	ds_swizzle_b32 v7, v6 offset:swizzle(SWAP,16)
	v_mov_b32_e32 v18, 0x358637bd
	s_mov_b32 s87, s27
	v_lshl_add_u64 v[4:5], v[82:83], 0, s[86:87]
	v_lshl_add_u64 v[16:17], v[4:5], 0, v[80:81]
	s_waitcnt lgkmcnt(0)
; __device__ __forceinline__ unsigned cvtpk(float lo, float hi) { f32x2 v = {lo, hi}; bf16x2_t b = __builtin_convertvector(v, bf16x2_t); return __builtin_bit_cast(unsigned, b); }
; __device__ __forceinline__ float bflo(unsigned u) { return __uint_as_float(u << 16); }
; __device__ __forceinline__ float bfhi(unsigned u) { return __uint_as_float(u & 0xffff0000u); }
; template <bool DIFF>
; __device__ __forceinline__ void attn_item(LAS unsigned char* lds, const bf16_t* Z, bf16_t* MIX, int b, int h, int t, float lam, float shift, const float* gain, int tid, int wid, int lane) {
;     ...
;     const float r = rsqrtf(ss * (1.0f / 128.0f) + EPS) * (DIFF ? 0.8f : 1.0f);
;     const int row = row0 + q16;
;     const bf16_t* gp = Z + (size_t)row * DIN + gcol + 4 * quad;
;     bf16_t* op = MIX + (size_t)row * DM + (DIFF ? 1024 : 0) + 128 * h + 4 * quad;
; #pragma unroll
;     for (int eb = 0; eb < 8; ++eb) {
;         const u32x2 gw = *(const u32x2*)(gp + 16 * eb);
;         const f32x4 gn = *(const f32x4*)(gain + 16 * eb + 4 * quad);
;         u32x2 w; w.x = cvtpk(O[0][eb][0] * r * gn.x * bflo(gw.x), O[0][eb][1] * r * gn.y * bfhi(gw.x));
;         w.y = cvtpk(O[0][eb][2] * r * gn.z * bflo(gw.y), O[0][eb][3] * r * gn.w * bfhi(gw.y));
;         *(u32x2*)(op + 16 * eb) = w;
	v_add_f32_e32 v6, v6, v7
	v_mov_b32_e32 v7, v6
	s_nop 1
	v_permlane32_swap_b32_e32 v6, v7
	v_add_f32_e32 v6, v6, v7
	v_fmamk_f32 v6, v6, 0x3c000000, v18
	v_mul_f32_e32 v7, 0x4b800000, v6
	v_cmp_gt_f32_e32 vcc, s42, v6
	s_nop 1
	v_cndmask_b32_e32 v6, v6, v7, vcc
	v_rsq_f32_e32 v24, v6
	s_nop 0
	v_mul_f32_e32 v25, 0x45800000, v24
	v_cndmask_b32_e32 v24, v24, v25, vcc
	v_mul_f32_e32 v24, 0x3f4ccccd, v24
	s_waitcnt vmcnt(0)
	v_permlane16_swap_b32_e32 v116, v118
	v_permlane16_swap_b32_e32 v117, v119
	v_permlane16_swap_b32_e32 v120, v122
	v_permlane16_swap_b32_e32 v121, v123
	v_permlane16_swap_b32_e32 v132, v134
	v_permlane16_swap_b32_e32 v133, v135
	v_permlane16_swap_b32_e32 v136, v138
	v_permlane16_swap_b32_e32 v137, v139
	v_mbcnt_lo_u32_b32 v150, -1, 0
	v_mbcnt_hi_u32_b32 v150, -1, v150
	v_and_b32_e32 v150, 16, v150
	v_lshrrev_b32_e32 v151, 1, v150
	v_add_u32_e32 v150, v150, v151
	v_mov_b32_e32 v151, 0
	v_lshl_add_u64 v[148:149], v[16:17], 0, v[150:151]
	v_pk_mul_f32 v[56:57], v[56:57], v[24:25] op_sel_hi:[1,0]
	v_pk_mul_f32 v[58:59], v[58:59], v[24:25] op_sel_hi:[1,0]
	v_lshlrev_b32_e32 v60, 16, v116
	v_and_b32_e32 v61, 0xffff0000, v116
	v_lshlrev_b32_e32 v62, 16, v117
	v_and_b32_e32 v63, 0xffff0000, v117
	v_pk_mul_f32 v[56:57], v[84:85], v[56:57]
	v_pk_mul_f32 v[58:59], v[86:87], v[58:59]
	v_pk_mul_f32 v[56:57], v[56:57], v[60:61]
	v_pk_mul_f32 v[58:59], v[58:59], v[62:63]
	v_cvt_pk_bf16_f32 v56, v56, v57
	v_cvt_pk_bf16_f32 v57, v58, v59
	v_pk_mul_f32 v[52:53], v[52:53], v[24:25] op_sel_hi:[1,0]
	v_pk_mul_f32 v[54:55], v[54:55], v[24:25] op_sel_hi:[1,0]
	v_lshlrev_b32_e32 v40, 16, v118
	v_and_b32_e32 v41, 0xffff0000, v118
	v_lshlrev_b32_e32 v42, 16, v119
	v_and_b32_e32 v43, 0xffff0000, v119
	v_pk_mul_f32 v[52:53], v[88:89], v[52:53]
	v_pk_mul_f32 v[54:55], v[90:91], v[54:55]
	v_pk_mul_f32 v[52:53], v[52:53], v[40:41]
	v_pk_mul_f32 v[54:55], v[54:55], v[42:43]
	v_cvt_pk_bf16_f32 v58, v52, v53
	v_cvt_pk_bf16_f32 v59, v54, v55
	s_nop 1
	v_permlane16_swap_b32_e32 v56, v58
	v_permlane16_swap_b32_e32 v57, v59
	global_store_dwordx4 v[148:149], v[56:59], off offset:2048
	v_pk_mul_f32 v[44:45], v[44:45], v[24:25] op_sel_hi:[1,0]
	v_pk_mul_f32 v[46:47], v[46:47], v[24:25] op_sel_hi:[1,0]
	v_lshlrev_b32_e32 v60, 16, v120
	v_and_b32_e32 v61, 0xffff0000, v120
	v_lshlrev_b32_e32 v62, 16, v121
	v_and_b32_e32 v63, 0xffff0000, v121
	v_pk_mul_f32 v[44:45], v[92:93], v[44:45]
	v_pk_mul_f32 v[46:47], v[94:95], v[46:47]
	v_pk_mul_f32 v[44:45], v[44:45], v[60:61]
	v_pk_mul_f32 v[46:47], v[46:47], v[62:63]
	v_cvt_pk_bf16_f32 v44, v44, v45
	v_cvt_pk_bf16_f32 v45, v46, v47
	v_pk_mul_f32 v[36:37], v[36:37], v[24:25] op_sel_hi:[1,0]
	v_pk_mul_f32 v[38:39], v[38:39], v[24:25] op_sel_hi:[1,0]
	v_lshlrev_b32_e32 v40, 16, v122
	v_and_b32_e32 v41, 0xffff0000, v122
	v_lshlrev_b32_e32 v42, 16, v123
	v_and_b32_e32 v43, 0xffff0000, v123
	v_pk_mul_f32 v[36:37], v[96:97], v[36:37]
	v_pk_mul_f32 v[38:39], v[98:99], v[38:39]
	v_pk_mul_f32 v[36:37], v[36:37], v[40:41]
	v_pk_mul_f32 v[38:39], v[38:39], v[42:43]
	v_cvt_pk_bf16_f32 v46, v36, v37
	v_cvt_pk_bf16_f32 v47, v38, v39
	s_nop 1
	v_permlane16_swap_b32_e32 v44, v46
	v_permlane16_swap_b32_e32 v45, v47
	global_store_dwordx4 v[148:149], v[44:47], off offset:2112
	v_pk_mul_f32 v[28:29], v[28:29], v[24:25] op_sel_hi:[1,0]
	v_pk_mul_f32 v[30:31], v[30:31], v[24:25] op_sel_hi:[1,0]
	v_lshlrev_b32_e32 v60, 16, v132
	v_and_b32_e32 v61, 0xffff0000, v132
	v_lshlrev_b32_e32 v62, 16, v133
	v_and_b32_e32 v63, 0xffff0000, v133
	v_pk_mul_f32 v[28:29], v[100:101], v[28:29]
	v_pk_mul_f32 v[30:31], v[102:103], v[30:31]
	v_pk_mul_f32 v[28:29], v[28:29], v[60:61]
	v_pk_mul_f32 v[30:31], v[30:31], v[62:63]
	v_cvt_pk_bf16_f32 v28, v28, v29
	v_cvt_pk_bf16_f32 v29, v30, v31
	v_pk_mul_f32 v[20:21], v[20:21], v[24:25] op_sel_hi:[1,0]
	v_pk_mul_f32 v[22:23], v[22:23], v[24:25] op_sel_hi:[1,0]
	v_lshlrev_b32_e32 v40, 16, v134
	v_and_b32_e32 v41, 0xffff0000, v134
	v_lshlrev_b32_e32 v42, 16, v135
	v_and_b32_e32 v43, 0xffff0000, v135
	v_pk_mul_f32 v[20:21], v[104:105], v[20:21]
	v_pk_mul_f32 v[22:23], v[106:107], v[22:23]
	v_pk_mul_f32 v[20:21], v[20:21], v[40:41]
	v_pk_mul_f32 v[22:23], v[22:23], v[42:43]
	v_cvt_pk_bf16_f32 v30, v20, v21
	v_cvt_pk_bf16_f32 v31, v22, v23
	s_nop 1
	v_permlane16_swap_b32_e32 v28, v30
	v_permlane16_swap_b32_e32 v29, v31
	global_store_dwordx4 v[148:149], v[28:31], off offset:2176
	v_pk_mul_f32 v[12:13], v[12:13], v[24:25] op_sel_hi:[1,0]
	v_pk_mul_f32 v[14:15], v[14:15], v[24:25] op_sel_hi:[1,0]
	v_lshlrev_b32_e32 v60, 16, v136
	v_and_b32_e32 v61, 0xffff0000, v136
	v_lshlrev_b32_e32 v62, 16, v137
	v_and_b32_e32 v63, 0xffff0000, v137
	v_pk_mul_f32 v[12:13], v[108:109], v[12:13]
	v_pk_mul_f32 v[14:15], v[110:111], v[14:15]
	v_pk_mul_f32 v[12:13], v[12:13], v[60:61]
	v_pk_mul_f32 v[14:15], v[14:15], v[62:63]
	v_cvt_pk_bf16_f32 v12, v12, v13
	v_cvt_pk_bf16_f32 v13, v14, v15
	v_pk_mul_f32 v[8:9], v[8:9], v[24:25] op_sel_hi:[1,0]
	v_pk_mul_f32 v[10:11], v[10:11], v[24:25] op_sel_hi:[1,0]
	v_lshlrev_b32_e32 v40, 16, v138
	v_and_b32_e32 v41, 0xffff0000, v138
	v_lshlrev_b32_e32 v42, 16, v139
	v_and_b32_e32 v43, 0xffff0000, v139
	v_pk_mul_f32 v[8:9], v[112:113], v[8:9]
	v_pk_mul_f32 v[10:11], v[114:115], v[10:11]
	v_pk_mul_f32 v[8:9], v[8:9], v[40:41]
	v_pk_mul_f32 v[10:11], v[10:11], v[42:43]
	v_cvt_pk_bf16_f32 v14, v8, v9
	v_cvt_pk_bf16_f32 v15, v10, v11
	s_nop 1
	v_permlane16_swap_b32_e32 v12, v14
	v_permlane16_swap_b32_e32 v13, v15
	global_store_dwordx4 v[148:149], v[12:15], off offset:2240
	s_nop 1
	v_mov_b32_e32 v15, v183
	s_cmp_lg_u32 s98, 0
	s_cbranch_scc1 .Lp2_item_done
	s_cmp_lt_i32 s9, 3
	s_cbranch_scc1 .LBB0_579
	s_cmp_lt_i32 s9, 4
	s_cbranch_scc1 .LBB0_580
	s_cmp_lt_i32 s9, 5
	s_cbranch_scc1 .LBB0_581
	s_cmp_lg_u32 s9, 5
	s_cbranch_scc0 .LBB0_582
	s_cmp_eq_u32 s9, 6
	s_cselect_b64 vcc, -1, 0
	v_mov_b32_e32 v4, 0xba38b001
	v_mov_b32_e32 v5, 0xbab8b5c7
	v_cndmask_b32_e32 v12, v4, v5, vcc
	s_cbranch_execz .LBB0_583
	s_branch .LBB0_584

; __device__ __forceinline__ int lane_id() { return (int)__builtin_amdgcn_mbcnt_hi(~0u, __builtin_amdgcn_mbcnt_lo(~0u, 0u)); }
; __device__ __forceinline__ void ret_pair(LAS unsigned char* lds, const bf16_t* Z, bf16_t* MIX, int b, int h, int tA, int tB, const float* gain, int wid) {
;     ...
;     int lf = lane_id(); asm volatile("" : "+v"(lf)); const int q16f = lf & 15, quadf = (lf >> 4) & 3;
; #pragma unroll
;     for (int which = 0; which < 2; ++which) {
;         f32x4 (&O)[8] = which ? OB : OA;
;         float ss = 0.f;
; #pragma unroll
;         for (int eb = 0; eb < 8; ++eb)
; #pragma unroll
;             for (int i = 0; i < 4; ++i) ss += O[eb][i] * O[eb][i];
;         ss = quad_sum(ss);
;         const float r = rsqrtf(ss * (1.0f / 128.0f) + EPS);
;         const int row = (which ? rowB0 : rowA0) + q16f;
;         const bf16_t* gp = Z + (size_t)row * DIN + gcol + 4 * quadf;
;         bf16_t* op = MIX + (size_t)row * DM + 128 * h + 4 * quadf;
; #pragma unroll
;         for (int eb = 0; eb < 8; ++eb) {
;             const u32x2 gw = *(const u32x2*)(gp + 16 * eb);
;             const f32x4 gn = *(const f32x4*)(gain + 16 * eb + 4 * quadf);
.LBB0_640:
	s_lshl_b32 s0, s80, 2
	v_readlane_b32 s1, v254, 24
	s_add_u32 s0, s1, s0
	v_readlane_b32 s1, v254, 23
	v_readlane_b32 s2, v255, 3
	s_waitcnt lgkmcnt(0)
	v_mov_b32_e32 v4, v183
	s_addc_u32 s1, s1, 0
	s_add_i32 s4, s2, 1
	s_add_u32 s2, s30, s86
	v_and_b32_e32 v93, 15, v4
	v_lshrrev_b32_e32 v4, 2, v4
	s_addc_u32 s3, s31, 0
	v_and_b32_e32 v4, 12, v4
	v_lshlrev_b32_e32 v180, 1, v4
	v_lshlrev_b32_e32 v4, 2, v4
	v_mov_b32_e32 v5, v181
	v_or_b32_e32 v32, s5, v93
	v_mov_b64_e32 v[6:7], s[2:3]
	v_lshl_add_u64 v[4:5], s[0:1], 0, v[4:5]
	v_readlane_b32 s3, v255, 7
	s_mov_b64 s[6:7], 0x1000
	v_mad_i64_i32 v[8:9], vcc, v32, s36, v[6:7]
	v_mov_b32_e32 v29, v181
	v_or_b32_e32 v30, s3, v93
	v_lshl_add_u64 v[10:11], v[8:9], 0, v[180:181]
	v_mad_i64_i32 v[6:7], vcc, v30, s36, v[6:7]
	v_lshl_add_u64 v[10:11], v[10:11], 0, s[6:7]
	v_lshl_add_u64 v[6:7], v[6:7], 0, v[180:181]
	s_add_u32 s0, s88, s86
	s_addc_u32 s1, s89, 0
	v_lshl_add_u64 v[6:7], v[6:7], 0, s[6:7]
	v_mbcnt_lo_u32_b32 v178, -1, 0
	v_mbcnt_hi_u32_b32 v178, -1, v178
	v_and_b32_e32 v178, 16, v178
	v_lshrrev_b32_e32 v179, 1, v178
	v_add_u32_e32 v178, v178, v179
	v_mov_b32_e32 v179, 0
	v_lshl_add_u64 v[170:171], v[10:11], 0, v[178:179]
	v_lshl_add_u64 v[172:173], v[6:7], 0, v[178:179]
	global_load_dwordx4 v[96:99], v[4:5], off
	global_load_dwordx4 v[134:137], v[170:171], off
	global_load_dwordx4 v[150:153], v[172:173], off
	global_load_dwordx4 v[100:103], v[4:5], off offset:64
	global_load_dwordx4 v[104:107], v[4:5], off offset:128
	global_load_dwordx4 v[138:141], v[170:171], off offset:64
	global_load_dwordx4 v[154:157], v[172:173], off offset:64
	global_load_dwordx4 v[108:111], v[4:5], off offset:192
	global_load_dwordx4 v[112:115], v[4:5], off offset:256
	global_load_dwordx4 v[142:145], v[170:171], off offset:128
	global_load_dwordx4 v[158:161], v[172:173], off offset:128
	global_load_dwordx4 v[116:119], v[4:5], off offset:320
	global_load_dwordx4 v[120:123], v[4:5], off offset:384
	global_load_dwordx4 v[146:149], v[170:171], off offset:192
	global_load_dwordx4 v[162:165], v[172:173], off offset:192
	global_load_dwordx4 v[124:127], v[4:5], off offset:448
	v_lshl_add_u64 v[8:9], s[0:1], 0, v[180:181]
	v_mov_b32_e32 v28, v32
	v_mov_b32_e32 v31, v181
	v_lshlrev_b64 v[28:29], 12, v[28:29]
	v_lshlrev_b64 v[30:31], 12, v[30:31]
	v_lshl_add_u64 v[166:167], v[8:9], 0, v[28:29]
	v_lshl_add_u64 v[168:169], v[8:9], 0, v[30:31]
	v_mul_f32_e32 v33, v81, v81
	v_fmac_f32_e32 v33, v80, v80
	v_fmac_f32_e32 v33, v82, v82
	v_fmac_f32_e32 v33, v83, v83
	v_fmac_f32_e32 v33, v76, v76
	v_fmac_f32_e32 v33, v77, v77
	v_fmac_f32_e32 v33, v78, v78
	v_fmac_f32_e32 v33, v79, v79
	v_fmac_f32_e32 v33, v72, v72
	v_fmac_f32_e32 v33, v73, v73
	v_fmac_f32_e32 v33, v74, v74
	v_fmac_f32_e32 v33, v75, v75
	v_fmac_f32_e32 v33, v68, v68
	v_fmac_f32_e32 v33, v69, v69
	v_fmac_f32_e32 v33, v70, v70
	v_fmac_f32_e32 v33, v71, v71
	v_fmac_f32_e32 v33, v64, v64
	v_fmac_f32_e32 v33, v65, v65
	v_fmac_f32_e32 v33, v66, v66
	v_fmac_f32_e32 v33, v67, v67
	v_fmac_f32_e32 v33, v60, v60
	v_fmac_f32_e32 v33, v61, v61
	v_fmac_f32_e32 v33, v62, v62
	v_fmac_f32_e32 v33, v63, v63
	v_pk_mul_f32 v[84:85], v[56:57], v[56:57]
	v_pk_mul_f32 v[8:9], v[58:59], v[58:59]
	v_add_f32_e32 v33, v84, v33
	v_add_f32_e32 v33, v85, v33
	v_add_f32_e32 v8, v8, v33
	v_add_f32_e32 v33, v9, v8
	v_pk_mul_f32 v[84:85], v[52:53], v[52:53]
	v_pk_mul_f32 v[8:9], v[54:55], v[54:55]
	v_add_f32_e32 v33, v84, v33
	v_add_f32_e32 v33, v85, v33
	v_add_f32_e32 v8, v8, v33
	v_add_f32_e32 v33, v9, v8
	ds_swizzle_b32 v84, v33 offset:swizzle(SWAP,16)
	v_pk_mul_f32 v[90:91], v[16:17], v[16:17]
	v_pk_mul_f32 v[88:89], v[18:19], v[18:19]
	s_waitcnt lgkmcnt(0)
	v_add_f32_e32 v85, v33, v84
	v_mul_f32_e32 v84, v49, v49
	v_fmac_f32_e32 v84, v48, v48
	v_fmac_f32_e32 v84, v50, v50
	v_fmac_f32_e32 v84, v51, v51
	v_fmac_f32_e32 v84, v44, v44
	v_fmac_f32_e32 v84, v45, v45
	v_fmac_f32_e32 v84, v46, v46
	v_fmac_f32_e32 v84, v47, v47
	v_fmac_f32_e32 v84, v40, v40
	v_fmac_f32_e32 v84, v41, v41
	v_fmac_f32_e32 v84, v42, v42
	v_fmac_f32_e32 v84, v43, v43
	v_fmac_f32_e32 v84, v36, v36
	v_fmac_f32_e32 v84, v37, v37
	v_fmac_f32_e32 v84, v38, v38
	v_fmac_f32_e32 v84, v39, v39
	v_fmac_f32_e32 v84, v24, v24
	v_fmac_f32_e32 v84, v25, v25
	v_fmac_f32_e32 v84, v26, v26
	v_fmac_f32_e32 v84, v27, v27
	v_fmac_f32_e32 v84, v20, v20
	v_fmac_f32_e32 v84, v21, v21
	v_fmac_f32_e32 v84, v22, v22
	v_fmac_f32_e32 v84, v23, v23
	v_add_f32_e32 v84, v90, v84
	v_add_f32_e32 v84, v91, v84
	v_add_f32_e32 v84, v88, v84
	v_add_f32_e32 v84, v89, v84
	v_pk_mul_f32 v[90:91], v[12:13], v[12:13]
	v_pk_mul_f32 v[88:89], v[14:15], v[14:15]
	v_add_f32_e32 v84, v90, v84
	v_add_f32_e32 v84, v91, v84
	v_add_f32_e32 v84, v88, v84
	v_add_f32_e32 v84, v89, v84
	ds_swizzle_b32 v86, v84 offset:swizzle(SWAP,16)
	v_mov_b32_e32 v87, v85
	s_nop 1
	v_permlane32_swap_b32_e32 v85, v87
	s_waitcnt lgkmcnt(0)
	v_add_f32_e32 v84, v84, v86
	v_mov_b32_e32 v86, v84
	s_nop 1
	v_permlane32_swap_b32_e32 v84, v86
	v_pk_add_f32 v[84:85], v[84:85], v[86:87]
	s_brev_b32 s0, 60
	v_mov_b32_e32 v34, 0x358637bd
	v_pk_fma_f32 v[84:85], v[84:85], s[0:1], v[34:35] op_sel_hi:[1,0,0]
	s_mov_b32 s2, 0x800000
	v_mul_f32_e32 v34, 0x4b800000, v85
	v_cmp_gt_f32_e32 vcc, s2, v85
	v_mul_f32_e32 v35, 0x4b800000, v84
	v_cmp_gt_f32_e64 s[0:1], s2, v84
	v_cndmask_b32_e32 v34, v85, v34, vcc
	v_rsq_f32_e32 v85, v34
	v_cndmask_b32_e64 v35, v84, v35, s[0:1]
	v_rsq_f32_e32 v84, v35
	v_mul_f32_e32 v92, 0x45800000, v85
	v_cndmask_b32_e32 v92, v85, v92, vcc
	v_mul_f32_e32 v94, 0x45800000, v84
	v_cndmask_b32_e64 v94, v84, v94, s[0:1]
	s_mov_b32 s87, s27
	s_mov_b32 m0, s90
	s_mov_b32 s42, 0x800000
	s_mov_b32 s5, 0
	s_waitcnt vmcnt(0)
; __device__ __forceinline__ unsigned cvtpk(float lo, float hi) { f32x2 v = {lo, hi}; bf16x2_t b = __builtin_convertvector(v, bf16x2_t); return __builtin_bit_cast(unsigned, b); }
; __device__ __forceinline__ float bflo(unsigned u) { return __uint_as_float(u << 16); }
; __device__ __forceinline__ float bfhi(unsigned u) { return __uint_as_float(u & 0xffff0000u); }
; __device__ __forceinline__ void ret_pair(LAS unsigned char* lds, const bf16_t* Z, bf16_t* MIX, int b, int h, int tA, int tB, const float* gain, int wid) {
;     ...
; #pragma unroll
;         for (int eb = 0; eb < 8; ++eb) {
;             const u32x2 gw = *(const u32x2*)(gp + 16 * eb);
;             const f32x4 gn = *(const f32x4*)(gain + 16 * eb + 4 * quadf);
;             u32x2 w; w.x = cvtpk(O[eb][0] * r * gn.x * bflo(gw.x), O[eb][1] * r * gn.y * bfhi(gw.x));
;             w.y = cvtpk(O[eb][2] * r * gn.z * bflo(gw.y), O[eb][3] * r * gn.w * bfhi(gw.y));
;             *(u32x2*)(op + 16 * eb) = w;
;         }
	v_permlane16_swap_b32_e32 v134, v136
	v_permlane16_swap_b32_e32 v135, v137
	v_permlane16_swap_b32_e32 v150, v152
	v_permlane16_swap_b32_e32 v151, v153
	v_permlane16_swap_b32_e32 v138, v140
	v_permlane16_swap_b32_e32 v139, v141
	v_permlane16_swap_b32_e32 v154, v156
	v_permlane16_swap_b32_e32 v155, v157
	v_permlane16_swap_b32_e32 v142, v144
	v_permlane16_swap_b32_e32 v143, v145
	v_permlane16_swap_b32_e32 v158, v160
	v_permlane16_swap_b32_e32 v159, v161
	v_permlane16_swap_b32_e32 v146, v148
	v_permlane16_swap_b32_e32 v147, v149
	v_permlane16_swap_b32_e32 v162, v164
	v_permlane16_swap_b32_e32 v163, v165
	v_mbcnt_lo_u32_b32 v178, -1, 0
	v_mbcnt_hi_u32_b32 v178, -1, v178
	v_and_b32_e32 v178, 16, v178
	v_lshrrev_b32_e32 v179, 1, v178
	v_add_u32_e32 v178, v178, v179
	v_mov_b32_e32 v179, 0
	v_lshl_add_u64 v[174:175], v[166:167], 0, v[178:179]
	v_lshl_add_u64 v[176:177], v[168:169], 0, v[178:179]
	v_pk_mul_f32 v[80:81], v[80:81], v[92:93] op_sel_hi:[1,0]
	v_pk_mul_f32 v[82:83], v[82:83], v[92:93] op_sel_hi:[1,0]
	v_lshlrev_b32_e32 v28, 16, v134
	v_and_b32_e32 v29, 0xffff0000, v134
	v_lshlrev_b32_e32 v30, 16, v135
	v_and_b32_e32 v31, 0xffff0000, v135
	v_pk_mul_f32 v[80:81], v[96:97], v[80:81]
	v_pk_mul_f32 v[82:83], v[98:99], v[82:83]
	v_pk_mul_f32 v[80:81], v[80:81], v[28:29]
	v_pk_mul_f32 v[82:83], v[82:83], v[30:31]
	v_cvt_pk_bf16_f32 v80, v80, v81
	v_cvt_pk_bf16_f32 v81, v82, v83
	v_pk_mul_f32 v[76:77], v[76:77], v[92:93] op_sel_hi:[1,0]
	v_pk_mul_f32 v[78:79], v[78:79], v[92:93] op_sel_hi:[1,0]
	v_lshlrev_b32_e32 v170, 16, v136
	v_and_b32_e32 v171, 0xffff0000, v136
	v_lshlrev_b32_e32 v172, 16, v137
	v_and_b32_e32 v173, 0xffff0000, v137
	v_pk_mul_f32 v[76:77], v[100:101], v[76:77]
	v_pk_mul_f32 v[78:79], v[102:103], v[78:79]
	v_pk_mul_f32 v[76:77], v[76:77], v[170:171]
	v_pk_mul_f32 v[78:79], v[78:79], v[172:173]
	v_cvt_pk_bf16_f32 v82, v76, v77
	v_cvt_pk_bf16_f32 v83, v78, v79
	s_nop 1
	v_permlane16_swap_b32_e32 v80, v82
	v_permlane16_swap_b32_e32 v81, v83
	global_store_dwordx4 v[174:175], v[80:83], off
	v_pk_mul_f32 v[48:49], v[48:49], v[94:95] op_sel_hi:[1,0]
	v_pk_mul_f32 v[50:51], v[50:51], v[94:95] op_sel_hi:[1,0]
	v_lshlrev_b32_e32 v28, 16, v150
	v_and_b32_e32 v29, 0xffff0000, v150
	v_lshlrev_b32_e32 v30, 16, v151
	v_and_b32_e32 v31, 0xffff0000, v151
	v_pk_mul_f32 v[48:49], v[96:97], v[48:49]
	v_pk_mul_f32 v[50:51], v[98:99], v[50:51]
	v_pk_mul_f32 v[48:49], v[48:49], v[28:29]
	v_pk_mul_f32 v[50:51], v[50:51], v[30:31]
	v_cvt_pk_bf16_f32 v48, v48, v49
	v_cvt_pk_bf16_f32 v49, v50, v51
	v_pk_mul_f32 v[44:45], v[44:45], v[94:95] op_sel_hi:[1,0]
	v_pk_mul_f32 v[46:47], v[46:47], v[94:95] op_sel_hi:[1,0]
	v_lshlrev_b32_e32 v170, 16, v152
	v_and_b32_e32 v171, 0xffff0000, v152
	v_lshlrev_b32_e32 v172, 16, v153
	v_and_b32_e32 v173, 0xffff0000, v153
	v_pk_mul_f32 v[44:45], v[100:101], v[44:45]
	v_pk_mul_f32 v[46:47], v[102:103], v[46:47]
	v_pk_mul_f32 v[44:45], v[44:45], v[170:171]
	v_pk_mul_f32 v[46:47], v[46:47], v[172:173]
	v_cvt_pk_bf16_f32 v50, v44, v45
	v_cvt_pk_bf16_f32 v51, v46, v47
	s_nop 1
	v_permlane16_swap_b32_e32 v48, v50
	v_permlane16_swap_b32_e32 v49, v51
	global_store_dwordx4 v[176:177], v[48:51], off
	v_pk_mul_f32 v[72:73], v[72:73], v[92:93] op_sel_hi:[1,0]
	v_pk_mul_f32 v[74:75], v[74:75], v[92:93] op_sel_hi:[1,0]
	v_lshlrev_b32_e32 v28, 16, v138
	v_and_b32_e32 v29, 0xffff0000, v138
	v_lshlrev_b32_e32 v30, 16, v139
	v_and_b32_e32 v31, 0xffff0000, v139
	v_pk_mul_f32 v[72:73], v[104:105], v[72:73]
	v_pk_mul_f32 v[74:75], v[106:107], v[74:75]
	v_pk_mul_f32 v[72:73], v[72:73], v[28:29]
	v_pk_mul_f32 v[74:75], v[74:75], v[30:31]
	v_cvt_pk_bf16_f32 v72, v72, v73
	v_cvt_pk_bf16_f32 v73, v74, v75
	v_pk_mul_f32 v[68:69], v[68:69], v[92:93] op_sel_hi:[1,0]
	v_pk_mul_f32 v[70:71], v[70:71], v[92:93] op_sel_hi:[1,0]
	v_lshlrev_b32_e32 v170, 16, v140
	v_and_b32_e32 v171, 0xffff0000, v140
	v_lshlrev_b32_e32 v172, 16, v141
	v_and_b32_e32 v173, 0xffff0000, v141
	v_pk_mul_f32 v[68:69], v[108:109], v[68:69]
	v_pk_mul_f32 v[70:71], v[110:111], v[70:71]
	v_pk_mul_f32 v[68:69], v[68:69], v[170:171]
	v_pk_mul_f32 v[70:71], v[70:71], v[172:173]
	v_cvt_pk_bf16_f32 v74, v68, v69
	v_cvt_pk_bf16_f32 v75, v70, v71
	s_nop 1
	v_permlane16_swap_b32_e32 v72, v74
	v_permlane16_swap_b32_e32 v73, v75
	global_store_dwordx4 v[174:175], v[72:75], off offset:64
	v_pk_mul_f32 v[40:41], v[40:41], v[94:95] op_sel_hi:[1,0]
	v_pk_mul_f32 v[42:43], v[42:43], v[94:95] op_sel_hi:[1,0]
	v_lshlrev_b32_e32 v28, 16, v154
	v_and_b32_e32 v29, 0xffff0000, v154
	v_lshlrev_b32_e32 v30, 16, v155
	v_and_b32_e32 v31, 0xffff0000, v155
	v_pk_mul_f32 v[40:41], v[104:105], v[40:41]
	v_pk_mul_f32 v[42:43], v[106:107], v[42:43]
	v_pk_mul_f32 v[40:41], v[40:41], v[28:29]
	v_pk_mul_f32 v[42:43], v[42:43], v[30:31]
	v_cvt_pk_bf16_f32 v40, v40, v41
	v_cvt_pk_bf16_f32 v41, v42, v43
	v_pk_mul_f32 v[36:37], v[36:37], v[94:95] op_sel_hi:[1,0]
	v_pk_mul_f32 v[38:39], v[38:39], v[94:95] op_sel_hi:[1,0]
	v_lshlrev_b32_e32 v170, 16, v156
	v_and_b32_e32 v171, 0xffff0000, v156
	v_lshlrev_b32_e32 v172, 16, v157
	v_and_b32_e32 v173, 0xffff0000, v157
	v_pk_mul_f32 v[36:37], v[108:109], v[36:37]
	v_pk_mul_f32 v[38:39], v[110:111], v[38:39]
	v_pk_mul_f32 v[36:37], v[36:37], v[170:171]
	v_pk_mul_f32 v[38:39], v[38:39], v[172:173]
	v_cvt_pk_bf16_f32 v42, v36, v37
	v_cvt_pk_bf16_f32 v43, v38, v39
	s_nop 1
	v_permlane16_swap_b32_e32 v40, v42
	v_permlane16_swap_b32_e32 v41, v43
	global_store_dwordx4 v[176:177], v[40:43], off offset:64
	v_pk_mul_f32 v[64:65], v[64:65], v[92:93] op_sel_hi:[1,0]
; __device__ __forceinline__ unsigned cvtpk(float lo, float hi) { f32x2 v = {lo, hi}; bf16x2_t b = __builtin_convertvector(v, bf16x2_t); return __builtin_bit_cast(unsigned, b); }
; __device__ __forceinline__ float bflo(unsigned u) { return __uint_as_float(u << 16); }
; __device__ __forceinline__ float bfhi(unsigned u) { return __uint_as_float(u & 0xffff0000u); }
; __device__ __forceinline__ void ret_pair(LAS unsigned char* lds, const bf16_t* Z, bf16_t* MIX, int b, int h, int tA, int tB, const float* gain, int wid) {
;     ...
; #pragma unroll
;         for (int eb = 0; eb < 8; ++eb) {
;             const u32x2 gw = *(const u32x2*)(gp + 16 * eb);
;             const f32x4 gn = *(const f32x4*)(gain + 16 * eb + 4 * quadf);
;             u32x2 w; w.x = cvtpk(O[eb][0] * r * gn.x * bflo(gw.x), O[eb][1] * r * gn.y * bfhi(gw.x));
;             w.y = cvtpk(O[eb][2] * r * gn.z * bflo(gw.y), O[eb][3] * r * gn.w * bfhi(gw.y));
;             *(u32x2*)(op + 16 * eb) = w;
;         }
; __global__ void __launch_bounds__(NWAVES * 64, 2) fwd(Args args) {
;     ...
;         for (int pi = vcu; pi < 256; pi += G) {
;             const int bh = pi >> 3, tp = pi & 7, b = bh >> 3, h = bh & 7;
;             attn_item<true>(lds, Z, MIX, b, h, 15 - tp, lam, shift, subln, 0, wid, 0);
;             ret_pair(lds, Z, MIX, b, h, 15 - tp, tp, ret_gn + 128 * h, wid);
;             attn_item<true>(lds, Z, MIX, b, h, tp, lam, shift, subln, 0, wid, 0);
;         }
	v_pk_mul_f32 v[66:67], v[66:67], v[92:93] op_sel_hi:[1,0]
	v_lshlrev_b32_e32 v28, 16, v142
	v_and_b32_e32 v29, 0xffff0000, v142
	v_lshlrev_b32_e32 v30, 16, v143
	v_and_b32_e32 v31, 0xffff0000, v143
	v_pk_mul_f32 v[64:65], v[112:113], v[64:65]
	v_pk_mul_f32 v[66:67], v[114:115], v[66:67]
	v_pk_mul_f32 v[64:65], v[64:65], v[28:29]
	v_pk_mul_f32 v[66:67], v[66:67], v[30:31]
	v_cvt_pk_bf16_f32 v64, v64, v65
	v_cvt_pk_bf16_f32 v65, v66, v67
	v_pk_mul_f32 v[60:61], v[60:61], v[92:93] op_sel_hi:[1,0]
	v_pk_mul_f32 v[62:63], v[62:63], v[92:93] op_sel_hi:[1,0]
	v_lshlrev_b32_e32 v170, 16, v144
	v_and_b32_e32 v171, 0xffff0000, v144
	v_lshlrev_b32_e32 v172, 16, v145
	v_and_b32_e32 v173, 0xffff0000, v145
	v_pk_mul_f32 v[60:61], v[116:117], v[60:61]
	v_pk_mul_f32 v[62:63], v[118:119], v[62:63]
	v_pk_mul_f32 v[60:61], v[60:61], v[170:171]
	v_pk_mul_f32 v[62:63], v[62:63], v[172:173]
	v_cvt_pk_bf16_f32 v66, v60, v61
	v_cvt_pk_bf16_f32 v67, v62, v63
	s_nop 1
	v_permlane16_swap_b32_e32 v64, v66
	v_permlane16_swap_b32_e32 v65, v67
	global_store_dwordx4 v[174:175], v[64:67], off offset:128
	v_pk_mul_f32 v[24:25], v[24:25], v[94:95] op_sel_hi:[1,0]
	v_pk_mul_f32 v[26:27], v[26:27], v[94:95] op_sel_hi:[1,0]
	v_lshlrev_b32_e32 v28, 16, v158
	v_and_b32_e32 v29, 0xffff0000, v158
	v_lshlrev_b32_e32 v30, 16, v159
	v_and_b32_e32 v31, 0xffff0000, v159
	v_pk_mul_f32 v[24:25], v[112:113], v[24:25]
	v_pk_mul_f32 v[26:27], v[114:115], v[26:27]
	v_pk_mul_f32 v[24:25], v[24:25], v[28:29]
	v_pk_mul_f32 v[26:27], v[26:27], v[30:31]
	v_cvt_pk_bf16_f32 v24, v24, v25
	v_cvt_pk_bf16_f32 v25, v26, v27
	v_pk_mul_f32 v[20:21], v[20:21], v[94:95] op_sel_hi:[1,0]
	v_pk_mul_f32 v[22:23], v[22:23], v[94:95] op_sel_hi:[1,0]
	v_lshlrev_b32_e32 v170, 16, v160
	v_and_b32_e32 v171, 0xffff0000, v160
	v_lshlrev_b32_e32 v172, 16, v161
	v_and_b32_e32 v173, 0xffff0000, v161
	v_pk_mul_f32 v[20:21], v[116:117], v[20:21]
	v_pk_mul_f32 v[22:23], v[118:119], v[22:23]
	v_pk_mul_f32 v[20:21], v[20:21], v[170:171]
	v_pk_mul_f32 v[22:23], v[22:23], v[172:173]
	v_cvt_pk_bf16_f32 v26, v20, v21
	v_cvt_pk_bf16_f32 v27, v22, v23
	s_nop 1
	v_permlane16_swap_b32_e32 v24, v26
	v_permlane16_swap_b32_e32 v25, v27
	global_store_dwordx4 v[176:177], v[24:27], off offset:128
	v_pk_mul_f32 v[56:57], v[56:57], v[92:93] op_sel_hi:[1,0]
	v_pk_mul_f32 v[58:59], v[58:59], v[92:93] op_sel_hi:[1,0]
	v_lshlrev_b32_e32 v28, 16, v146
	v_and_b32_e32 v29, 0xffff0000, v146
	v_lshlrev_b32_e32 v30, 16, v147
	v_and_b32_e32 v31, 0xffff0000, v147
	v_pk_mul_f32 v[56:57], v[120:121], v[56:57]
	v_pk_mul_f32 v[58:59], v[122:123], v[58:59]
	v_pk_mul_f32 v[56:57], v[56:57], v[28:29]
	v_pk_mul_f32 v[58:59], v[58:59], v[30:31]
	v_cvt_pk_bf16_f32 v56, v56, v57
	v_cvt_pk_bf16_f32 v57, v58, v59
	v_pk_mul_f32 v[52:53], v[52:53], v[92:93] op_sel_hi:[1,0]
	v_pk_mul_f32 v[54:55], v[54:55], v[92:93] op_sel_hi:[1,0]
	v_lshlrev_b32_e32 v170, 16, v148
	v_and_b32_e32 v171, 0xffff0000, v148
	v_lshlrev_b32_e32 v172, 16, v149
	v_and_b32_e32 v173, 0xffff0000, v149
	v_pk_mul_f32 v[52:53], v[124:125], v[52:53]
	v_pk_mul_f32 v[54:55], v[126:127], v[54:55]
	v_pk_mul_f32 v[52:53], v[52:53], v[170:171]
	v_pk_mul_f32 v[54:55], v[54:55], v[172:173]
	v_cvt_pk_bf16_f32 v58, v52, v53
	v_cvt_pk_bf16_f32 v59, v54, v55
	s_nop 1
	v_permlane16_swap_b32_e32 v56, v58
	v_permlane16_swap_b32_e32 v57, v59
	global_store_dwordx4 v[174:175], v[56:59], off offset:192
	v_pk_mul_f32 v[16:17], v[16:17], v[94:95] op_sel_hi:[1,0]
	v_pk_mul_f32 v[18:19], v[18:19], v[94:95] op_sel_hi:[1,0]
	v_lshlrev_b32_e32 v28, 16, v162
	v_and_b32_e32 v29, 0xffff0000, v162
	v_lshlrev_b32_e32 v30, 16, v163
	v_and_b32_e32 v31, 0xffff0000, v163
	v_pk_mul_f32 v[16:17], v[120:121], v[16:17]
	v_pk_mul_f32 v[18:19], v[122:123], v[18:19]
	v_pk_mul_f32 v[16:17], v[16:17], v[28:29]
	v_pk_mul_f32 v[18:19], v[18:19], v[30:31]
	v_cvt_pk_bf16_f32 v16, v16, v17
	v_cvt_pk_bf16_f32 v17, v18, v19
	v_pk_mul_f32 v[12:13], v[12:13], v[94:95] op_sel_hi:[1,0]
	v_pk_mul_f32 v[14:15], v[14:15], v[94:95] op_sel_hi:[1,0]
	v_lshlrev_b32_e32 v170, 16, v164
	v_and_b32_e32 v171, 0xffff0000, v164
	v_lshlrev_b32_e32 v172, 16, v165
	v_and_b32_e32 v173, 0xffff0000, v165
	v_pk_mul_f32 v[12:13], v[124:125], v[12:13]
	v_pk_mul_f32 v[14:15], v[126:127], v[14:15]
	v_pk_mul_f32 v[12:13], v[12:13], v[170:171]
	v_pk_mul_f32 v[14:15], v[14:15], v[172:173]
	v_cvt_pk_bf16_f32 v18, v12, v13
	v_cvt_pk_bf16_f32 v19, v14, v15
	s_nop 1
	v_permlane16_swap_b32_e32 v16, v18
	v_permlane16_swap_b32_e32 v17, v19
	global_store_dwordx4 v[176:177], v[16:19], off offset:192
	s_nop 1
	v_readlane_b32 s17, v254, 44
	v_readlane_b32 s38, v254, 45
	v_readlane_b32 s39, v254, 46
	v_readlane_b32 s18, v254, 47
	v_readlane_b32 s40, v254, 48
	v_readlane_b32 s41, v254, 49
	v_readlane_b32 s43, v254, 50
	v_readlane_b32 s28, v254, 36
	v_readlane_b32 s30, v254, 37
	v_readlane_b32 s31, v254, 38
	v_readlane_b32 s88, v254, 39
	v_readlane_b32 s89, v254, 40
	v_readlane_b32 s29, v254, 41
	v_readlane_b32 s34, v254, 42
	v_readlane_b32 s35, v254, 43
	v_readlane_b32 s66, v254, 33
	v_readlane_b32 s84, v254, 34
	v_readlane_b32 s85, v254, 35
	v_readlane_b32 s78, v254, 32
	s_mov_b32 s27, 0
	s_movk_i32 s36, 0x3800
	s_mov_b64 s[14:15], 0x1800
	s_movk_i32 s16, 0x1000
	s_movk_i32 s37, 0x1c00
	s_mov_b64 s[96:97], 0x80
	s_movk_i32 s67, 0xe0
	s_movk_i32 s73, 0x60
	s_movk_i32 s74, 0x80
	s_movk_i32 s75, 0xa0
	s_movk_i32 s79, 0xc0
	s_mov_b64 s[92:93], 0x3000
	s_mov_b32 s42, 0x800000
	v_readlane_b32 s44, v255, 2
	v_readlane_b32 s2, v254, 51
	s_mov_b32 s98, 1
	s_mov_b32 s99, 0x01234567
	s_branch .LBB0_565
